# accumulator zeroing between GEMM units done by 7 zero-operand 32x32x16 bf16 MFMAs plus 8 v_mov_b64 instead of 64 v_mov_b64 (idle matrix pipe), on top of v59
# baseline (speedup 1.0000x reference)
.LBB0_59:
	s_or_b64 exec, exec, s[34:35]
	s_and_b64 vcc, exec, s[6:7]
	s_mov_b64 s[6:7], -1
	s_cbranch_vccnz .LBB0_40
	s_andn2_b64 vcc, exec, s[48:49]
	s_waitcnt lgkmcnt(0)
	v_mov_b64 v[126:127], 0
	v_mov_b64 v[128:129], 0
	v_mov_b64 v[118:119], 0
	v_mov_b64 v[120:121], 0
	v_mov_b64 v[122:123], 0
	v_mov_b64 v[124:125], 0
	v_mfma_f32_32x32x16_bf16 v[102:117], v[126:129], v[126:129], 0
	v_mfma_f32_32x32x16_bf16 v[86:101], v[126:129], v[126:129], 0
	v_mfma_f32_32x32x16_bf16 v[70:85], v[126:129], v[126:129], 0
	v_mfma_f32_32x32x16_bf16 v[54:69], v[126:129], v[126:129], 0
	v_mfma_f32_32x32x16_bf16 v[38:53], v[126:129], v[126:129], 0
	v_mfma_f32_32x32x16_bf16 v[22:37], v[126:129], v[126:129], 0
	v_mfma_f32_32x32x16_bf16 v[6:21], v[126:129], v[126:129], 0
	v_mov_b64 v[2:3], 0
	v_mov_b64 v[4:5], 0
	s_cbranch_vccnz .LBB0_39
	s_barrier
	s_branch .LBB0_39

.Leg_fin:
	s_movk_i32 s8, 0xfa00
	s_mov_b32 s9, -1
	s_mov_b64 s[0:1], -1
	s_and_b64 vcc, exec, s[40:41]
	s_cbranch_vccnz .LBB0_194
	s_andn2_b64 vcc, exec, s[24:25]
	v_mov_b64 v[126:127], 0
	v_mov_b64 v[128:129], 0
	v_mov_b64 v[118:119], 0
	v_mov_b64 v[120:121], 0
	v_mov_b64 v[122:123], 0
	v_mov_b64 v[124:125], 0
	v_mfma_f32_32x32x16_bf16 v[102:117], v[126:129], v[126:129], 0
	v_mfma_f32_32x32x16_bf16 v[86:101], v[126:129], v[126:129], 0
	v_mfma_f32_32x32x16_bf16 v[70:85], v[126:129], v[126:129], 0
	v_mfma_f32_32x32x16_bf16 v[54:69], v[126:129], v[126:129], 0
	v_mfma_f32_32x32x16_bf16 v[38:53], v[126:129], v[126:129], 0
	v_mfma_f32_32x32x16_bf16 v[22:37], v[126:129], v[126:129], 0
	v_mfma_f32_32x32x16_bf16 v[6:21], v[126:129], v[126:129], 0
	v_mov_b64 v[2:3], 0
	v_mov_b64 v[4:5], 0
	s_cbranch_vccnz .LBB0_193
	s_barrier
	s_branch .LBB0_193

.LBB0_376:
	s_add_u32 s8, s75, 0x40080
	s_addc_u32 s9, s23, 0
	s_mov_b32 m0, s69
	s_nop 0
	global_load_lds_dwordx4 v136, s[8:9]
	v_lshl_add_u32 v147, s74, 10, v143
	s_mov_b32 m0, s70
	s_nop 0
	global_load_lds_dwordx4 v138, s[8:9]
	ds_read_b32 v148, v147
	v_lshl_or_b32 v132, s36, 8, v144
	v_lshl_add_u32 v149, s38, 8, v142
	v_ashrrev_i32_e32 v133, 31, v132
	v_mov_b64_e32 v[130:131], s[26:27]
	v_mad_i64_i32 v[150:151], s[8:9], v149, s83, v[130:131]
	v_lshlrev_b64 v[132:133], 1, v[132:133]
	v_lshl_add_u64 v[150:151], v[150:151], 0, v[132:133]
	s_waitcnt lgkmcnt(0)
	v_pk_mul_f32 v[128:129], v[128:129], v[148:149] op_sel_hi:[1,0]
	v_pk_mul_f32 v[126:127], v[126:127], v[148:149] op_sel_hi:[1,0]
	v_pk_mul_f32 v[152:153], v[124:125], v[148:149] op_sel_hi:[1,0]
	v_pk_mul_f32 v[124:125], v[122:123], v[148:149] op_sel_hi:[1,0]
	v_cvt_pk_bf16_f32 v122, v126, v127
	v_cvt_pk_bf16_f32 v123, v128, v129
	v_pk_mul_f32 v[118:119], v[118:119], v[148:149] op_sel_hi:[1,0]
	v_cvt_pk_bf16_f32 v124, v124, v125
	v_cvt_pk_bf16_f32 v125, v152, v153
	global_store_dwordx4 v[150:151], v[122:125], off
	v_pk_mul_f32 v[120:121], v[120:121], v[148:149] op_sel_hi:[1,0]
	s_andn2_b64 vcc, exec, s[4:5]
	v_pk_mul_f32 v[122:123], v[116:117], v[148:149] op_sel_hi:[1,0]
	v_pk_mul_f32 v[116:117], v[114:115], v[148:149] op_sel_hi:[1,0]
	v_cvt_pk_bf16_f32 v114, v118, v119
	v_cvt_pk_bf16_f32 v115, v120, v121
	s_mov_b64 s[4:5], -1
	v_cvt_pk_bf16_f32 v116, v116, v117
	v_cvt_pk_bf16_f32 v117, v122, v123
	global_store_dwordx4 v[150:151], v[114:117], off offset:256
	ds_read_b32 v114, v147 offset:64
	s_nop 0
	v_or_b32_e32 v115, 16, v149
	v_mad_i64_i32 v[116:117], s[8:9], v115, s83, v[130:131]
	v_lshl_add_u64 v[116:117], v[116:117], 0, v[132:133]
	s_waitcnt lgkmcnt(0)
	v_pk_mul_f32 v[112:113], v[112:113], v[114:115] op_sel_hi:[1,0]
	v_pk_mul_f32 v[110:111], v[110:111], v[114:115] op_sel_hi:[1,0]
	v_pk_mul_f32 v[118:119], v[108:109], v[114:115] op_sel_hi:[1,0]
	v_pk_mul_f32 v[108:109], v[106:107], v[114:115] op_sel_hi:[1,0]
	v_cvt_pk_bf16_f32 v106, v110, v111
	v_cvt_pk_bf16_f32 v107, v112, v113
	v_pk_mul_f32 v[102:103], v[102:103], v[114:115] op_sel_hi:[1,0]
	v_cvt_pk_bf16_f32 v108, v108, v109
	v_cvt_pk_bf16_f32 v109, v118, v119
	global_store_dwordx4 v[116:117], v[106:109], off
	v_pk_mul_f32 v[104:105], v[104:105], v[114:115] op_sel_hi:[1,0]
	s_nop 0
	v_pk_mul_f32 v[106:107], v[100:101], v[114:115] op_sel_hi:[1,0]
	v_pk_mul_f32 v[100:101], v[98:99], v[114:115] op_sel_hi:[1,0]
	v_cvt_pk_bf16_f32 v98, v102, v103
	v_cvt_pk_bf16_f32 v99, v104, v105
	s_nop 0
	v_cvt_pk_bf16_f32 v100, v100, v101
	v_cvt_pk_bf16_f32 v101, v106, v107
	global_store_dwordx4 v[116:117], v[98:101], off offset:256
	ds_read_b32 v98, v147 offset:128
	s_nop 0
	v_or_b32_e32 v99, 32, v149
	v_mad_i64_i32 v[100:101], s[8:9], v99, s83, v[130:131]
	v_lshl_add_u64 v[100:101], v[100:101], 0, v[132:133]
	s_waitcnt lgkmcnt(0)
	v_pk_mul_f32 v[96:97], v[96:97], v[98:99] op_sel_hi:[1,0]
	v_pk_mul_f32 v[94:95], v[94:95], v[98:99] op_sel_hi:[1,0]
	v_pk_mul_f32 v[102:103], v[92:93], v[98:99] op_sel_hi:[1,0]
	v_pk_mul_f32 v[92:93], v[90:91], v[98:99] op_sel_hi:[1,0]
	v_cvt_pk_bf16_f32 v90, v94, v95
	v_cvt_pk_bf16_f32 v91, v96, v97
	v_pk_mul_f32 v[86:87], v[86:87], v[98:99] op_sel_hi:[1,0]
	v_cvt_pk_bf16_f32 v92, v92, v93
	v_cvt_pk_bf16_f32 v93, v102, v103
	global_store_dwordx4 v[100:101], v[90:93], off
	v_pk_mul_f32 v[88:89], v[88:89], v[98:99] op_sel_hi:[1,0]
	s_nop 0
	v_pk_mul_f32 v[90:91], v[84:85], v[98:99] op_sel_hi:[1,0]
	v_pk_mul_f32 v[84:85], v[82:83], v[98:99] op_sel_hi:[1,0]
	v_cvt_pk_bf16_f32 v82, v86, v87
	v_cvt_pk_bf16_f32 v83, v88, v89
	s_nop 0
	v_cvt_pk_bf16_f32 v84, v84, v85
	v_cvt_pk_bf16_f32 v85, v90, v91
	global_store_dwordx4 v[100:101], v[82:85], off offset:256
	ds_read_b32 v82, v147 offset:192
	s_nop 0
	v_or_b32_e32 v83, 48, v149
	v_mad_i64_i32 v[84:85], s[8:9], v83, s83, v[130:131]
	v_lshl_add_u64 v[84:85], v[84:85], 0, v[132:133]
	s_waitcnt lgkmcnt(0)
	v_pk_mul_f32 v[80:81], v[80:81], v[82:83] op_sel_hi:[1,0]
	v_pk_mul_f32 v[78:79], v[78:79], v[82:83] op_sel_hi:[1,0]
	v_pk_mul_f32 v[86:87], v[76:77], v[82:83] op_sel_hi:[1,0]
	v_pk_mul_f32 v[76:77], v[74:75], v[82:83] op_sel_hi:[1,0]
	v_cvt_pk_bf16_f32 v74, v78, v79
	v_cvt_pk_bf16_f32 v75, v80, v81
	v_pk_mul_f32 v[70:71], v[70:71], v[82:83] op_sel_hi:[1,0]
	v_cvt_pk_bf16_f32 v76, v76, v77
	v_cvt_pk_bf16_f32 v77, v86, v87
	global_store_dwordx4 v[84:85], v[74:77], off
	v_pk_mul_f32 v[72:73], v[72:73], v[82:83] op_sel_hi:[1,0]
	s_nop 0
	v_pk_mul_f32 v[74:75], v[68:69], v[82:83] op_sel_hi:[1,0]
	v_pk_mul_f32 v[68:69], v[66:67], v[82:83] op_sel_hi:[1,0]
	v_cvt_pk_bf16_f32 v66, v70, v71
	v_cvt_pk_bf16_f32 v67, v72, v73
	s_nop 0
	v_cvt_pk_bf16_f32 v68, v68, v69
	v_cvt_pk_bf16_f32 v69, v74, v75
	global_store_dwordx4 v[84:85], v[66:69], off offset:256
	ds_read_b32 v66, v147 offset:512
	s_nop 0
	v_add_u32_e32 v67, 0x80, v149
	v_mad_i64_i32 v[68:69], s[8:9], v67, s83, v[130:131]
	v_lshl_add_u64 v[68:69], v[68:69], 0, v[132:133]
	s_waitcnt lgkmcnt(0)
	v_pk_mul_f32 v[64:65], v[64:65], v[66:67] op_sel_hi:[1,0]
	v_pk_mul_f32 v[62:63], v[62:63], v[66:67] op_sel_hi:[1,0]
	v_pk_mul_f32 v[70:71], v[60:61], v[66:67] op_sel_hi:[1,0]
	v_pk_mul_f32 v[60:61], v[58:59], v[66:67] op_sel_hi:[1,0]
	v_cvt_pk_bf16_f32 v58, v62, v63
	v_cvt_pk_bf16_f32 v59, v64, v65
	v_pk_mul_f32 v[54:55], v[54:55], v[66:67] op_sel_hi:[1,0]
	v_cvt_pk_bf16_f32 v60, v60, v61
	v_cvt_pk_bf16_f32 v61, v70, v71
	global_store_dwordx4 v[68:69], v[58:61], off
	v_pk_mul_f32 v[56:57], v[56:57], v[66:67] op_sel_hi:[1,0]
	s_nop 0
	v_pk_mul_f32 v[58:59], v[52:53], v[66:67] op_sel_hi:[1,0]
	v_pk_mul_f32 v[52:53], v[50:51], v[66:67] op_sel_hi:[1,0]
	v_cvt_pk_bf16_f32 v50, v54, v55
	v_cvt_pk_bf16_f32 v51, v56, v57
	s_nop 0
	v_cvt_pk_bf16_f32 v52, v52, v53
	v_cvt_pk_bf16_f32 v53, v58, v59
	global_store_dwordx4 v[68:69], v[50:53], off offset:256
	ds_read_b32 v50, v147 offset:576
	s_nop 0
	v_add_u32_e32 v51, 0x90, v149
	v_mad_i64_i32 v[52:53], s[8:9], v51, s83, v[130:131]
	v_lshl_add_u64 v[52:53], v[52:53], 0, v[132:133]
	s_waitcnt lgkmcnt(0)
	v_pk_mul_f32 v[48:49], v[48:49], v[50:51] op_sel_hi:[1,0]
	v_pk_mul_f32 v[46:47], v[46:47], v[50:51] op_sel_hi:[1,0]
	v_pk_mul_f32 v[54:55], v[44:45], v[50:51] op_sel_hi:[1,0]
	v_pk_mul_f32 v[44:45], v[42:43], v[50:51] op_sel_hi:[1,0]
	v_cvt_pk_bf16_f32 v42, v46, v47
	v_cvt_pk_bf16_f32 v43, v48, v49
	v_pk_mul_f32 v[38:39], v[38:39], v[50:51] op_sel_hi:[1,0]
	v_cvt_pk_bf16_f32 v44, v44, v45
	v_cvt_pk_bf16_f32 v45, v54, v55
	global_store_dwordx4 v[52:53], v[42:45], off
	v_pk_mul_f32 v[40:41], v[40:41], v[50:51] op_sel_hi:[1,0]
	s_nop 0
	v_pk_mul_f32 v[42:43], v[36:37], v[50:51] op_sel_hi:[1,0]
	v_pk_mul_f32 v[36:37], v[34:35], v[50:51] op_sel_hi:[1,0]
	v_cvt_pk_bf16_f32 v34, v38, v39
	v_cvt_pk_bf16_f32 v35, v40, v41
	s_nop 0
	v_cvt_pk_bf16_f32 v36, v36, v37
	v_cvt_pk_bf16_f32 v37, v42, v43
	global_store_dwordx4 v[52:53], v[34:37], off offset:256
	ds_read_b32 v34, v147 offset:640
	s_nop 0
	v_add_u32_e32 v35, 0xa0, v149
	v_mad_i64_i32 v[36:37], s[8:9], v35, s83, v[130:131]
	v_lshl_add_u64 v[36:37], v[36:37], 0, v[132:133]
	s_waitcnt lgkmcnt(0)
	v_pk_mul_f32 v[32:33], v[32:33], v[34:35] op_sel_hi:[1,0]
	v_pk_mul_f32 v[30:31], v[30:31], v[34:35] op_sel_hi:[1,0]
	v_pk_mul_f32 v[38:39], v[28:29], v[34:35] op_sel_hi:[1,0]
	v_pk_mul_f32 v[28:29], v[26:27], v[34:35] op_sel_hi:[1,0]
	v_cvt_pk_bf16_f32 v26, v30, v31
	v_cvt_pk_bf16_f32 v27, v32, v33
	v_pk_mul_f32 v[22:23], v[22:23], v[34:35] op_sel_hi:[1,0]
	v_cvt_pk_bf16_f32 v28, v28, v29
	v_cvt_pk_bf16_f32 v29, v38, v39
	global_store_dwordx4 v[36:37], v[26:29], off
	v_pk_mul_f32 v[24:25], v[24:25], v[34:35] op_sel_hi:[1,0]
	s_nop 0
	v_pk_mul_f32 v[26:27], v[20:21], v[34:35] op_sel_hi:[1,0]
	v_pk_mul_f32 v[20:21], v[18:19], v[34:35] op_sel_hi:[1,0]
	v_cvt_pk_bf16_f32 v18, v22, v23
	v_cvt_pk_bf16_f32 v19, v24, v25
	s_nop 0
	v_cvt_pk_bf16_f32 v20, v20, v21
	v_cvt_pk_bf16_f32 v21, v26, v27
	global_store_dwordx4 v[36:37], v[18:21], off offset:256
	ds_read_b32 v18, v147 offset:704
	s_nop 0
	v_add_u32_e32 v19, 0xb0, v149
	v_mad_i64_i32 v[20:21], s[8:9], v19, s83, v[130:131]
	v_lshl_add_u64 v[20:21], v[20:21], 0, v[132:133]
	s_waitcnt lgkmcnt(0)
	v_pk_mul_f32 v[16:17], v[16:17], v[18:19] op_sel_hi:[1,0]
	v_pk_mul_f32 v[14:15], v[14:15], v[18:19] op_sel_hi:[1,0]
	v_pk_mul_f32 v[22:23], v[12:13], v[18:19] op_sel_hi:[1,0]
	v_pk_mul_f32 v[12:13], v[10:11], v[18:19] op_sel_hi:[1,0]
	v_cvt_pk_bf16_f32 v10, v14, v15
	v_cvt_pk_bf16_f32 v11, v16, v17
	v_pk_mul_f32 v[8:9], v[8:9], v[18:19] op_sel_hi:[1,0]
	v_cvt_pk_bf16_f32 v12, v12, v13
	v_cvt_pk_bf16_f32 v13, v22, v23
	global_store_dwordx4 v[20:21], v[10:13], off
	v_pk_mul_f32 v[6:7], v[6:7], v[18:19] op_sel_hi:[1,0]
	s_nop 0
	v_pk_mul_f32 v[10:11], v[4:5], v[18:19] op_sel_hi:[1,0]
	v_pk_mul_f32 v[4:5], v[2:3], v[18:19] op_sel_hi:[1,0]
	v_cvt_pk_bf16_f32 v2, v6, v7
	v_cvt_pk_bf16_f32 v3, v8, v9
	s_nop 0
	v_cvt_pk_bf16_f32 v4, v4, v5
	v_cvt_pk_bf16_f32 v5, v10, v11
	global_store_dwordx4 v[20:21], v[2:5], off offset:256
	s_cbranch_vccnz .LBB0_365
	s_andn2_b64 vcc, exec, s[6:7]
	v_mov_b64 v[126:127], 0
	v_mov_b64 v[128:129], 0
	v_mov_b64 v[118:119], 0
	v_mov_b64 v[120:121], 0
	v_mov_b64 v[122:123], 0
	v_mov_b64 v[124:125], 0
	v_mfma_f32_32x32x16_bf16 v[102:117], v[126:129], v[126:129], 0
	v_mfma_f32_32x32x16_bf16 v[86:101], v[126:129], v[126:129], 0
	v_mfma_f32_32x32x16_bf16 v[70:85], v[126:129], v[126:129], 0
	v_mfma_f32_32x32x16_bf16 v[54:69], v[126:129], v[126:129], 0
	v_mfma_f32_32x32x16_bf16 v[38:53], v[126:129], v[126:129], 0
	v_mfma_f32_32x32x16_bf16 v[22:37], v[126:129], v[126:129], 0
	v_mfma_f32_32x32x16_bf16 v[6:21], v[126:129], v[126:129], 0
	v_mov_b64 v[2:3], 0
	v_mov_b64 v[4:5], 0
	s_cbranch_vccnz .LBB0_364
	s_barrier
	s_branch .LBB0_364

.LBB0_462:
	s_add_u32 s8, s71, 0x40080
	s_addc_u32 s9, s27, 0
	s_mov_b32 m0, s66
	s_nop 0
	global_load_lds_dwordx4 v136, s[8:9]
	v_lshl_add_u32 v147, s70, 10, v133
	s_mov_b32 m0, s67
	s_nop 0
	global_load_lds_dwordx4 v138, s[8:9]
	ds_read_b32 v146, v147
	v_lshl_add_u32 v144, s38, 8, v132
	v_lshl_or_b32 v130, s69, 8, v141
	v_ashrrev_i32_e32 v145, 31, v144
	v_ashrrev_i32_e32 v131, 31, v130
	v_lshlrev_b64 v[148:149], 9, v[144:145]
	v_lshl_add_u64 v[148:149], s[20:21], 0, v[148:149]
	v_lshlrev_b64 v[150:151], 1, v[130:131]
	v_lshl_add_u64 v[130:131], v[148:149], 0, v[150:151]
	s_waitcnt lgkmcnt(0)
	v_pk_mul_f32 v[128:129], v[128:129], v[146:147] op_sel_hi:[1,0]
	v_pk_mul_f32 v[126:127], v[126:127], v[146:147] op_sel_hi:[1,0]
	v_pk_mul_f32 v[148:149], v[124:125], v[146:147] op_sel_hi:[1,0]
	v_pk_mul_f32 v[124:125], v[122:123], v[146:147] op_sel_hi:[1,0]
	v_cvt_pk_bf16_f32 v122, v126, v127
	v_cvt_pk_bf16_f32 v123, v128, v129
	v_pk_mul_f32 v[120:121], v[120:121], v[146:147] op_sel_hi:[1,0]
	v_cvt_pk_bf16_f32 v124, v124, v125
	v_cvt_pk_bf16_f32 v125, v148, v149
	global_store_dwordx4 v[130:131], v[122:125], off
	v_pk_mul_f32 v[118:119], v[118:119], v[146:147] op_sel_hi:[1,0]
	s_mov_b64 s[8:9], 0x10000
	v_pk_mul_f32 v[122:123], v[116:117], v[146:147] op_sel_hi:[1,0]
	v_pk_mul_f32 v[116:117], v[114:115], v[146:147] op_sel_hi:[1,0]
	v_cvt_pk_bf16_f32 v114, v118, v119
	v_cvt_pk_bf16_f32 v115, v120, v121
	s_mov_b32 s2, 0x14000
	v_cvt_pk_bf16_f32 v116, v116, v117
	v_cvt_pk_bf16_f32 v117, v122, v123
	global_store_dwordx4 v[130:131], v[114:117], off offset:256
	ds_read_b32 v116, v147 offset:64
	s_waitcnt lgkmcnt(0)
	v_pk_mul_f32 v[112:113], v[112:113], v[116:117] op_sel_hi:[1,0]
	v_or_b32_e32 v114, 16, v144
	v_ashrrev_i32_e32 v115, 31, v114
	v_lshlrev_b64 v[114:115], 9, v[114:115]
	v_lshl_add_u64 v[114:115], s[20:21], 0, v[114:115]
	v_lshl_add_u64 v[114:115], v[114:115], 0, v[150:151]
	v_pk_mul_f32 v[110:111], v[110:111], v[116:117] op_sel_hi:[1,0]
	v_pk_mul_f32 v[118:119], v[108:109], v[116:117] op_sel_hi:[1,0]
	v_pk_mul_f32 v[108:109], v[106:107], v[116:117] op_sel_hi:[1,0]
	v_cvt_pk_bf16_f32 v106, v110, v111
	v_cvt_pk_bf16_f32 v107, v112, v113
	v_pk_mul_f32 v[104:105], v[104:105], v[116:117] op_sel_hi:[1,0]
	v_cvt_pk_bf16_f32 v108, v108, v109
	v_cvt_pk_bf16_f32 v109, v118, v119
	global_store_dwordx4 v[114:115], v[106:109], off
	v_pk_mul_f32 v[102:103], v[102:103], v[116:117] op_sel_hi:[1,0]
	s_nop 0
	v_pk_mul_f32 v[106:107], v[100:101], v[116:117] op_sel_hi:[1,0]
	v_pk_mul_f32 v[100:101], v[98:99], v[116:117] op_sel_hi:[1,0]
	v_cvt_pk_bf16_f32 v98, v102, v103
	v_cvt_pk_bf16_f32 v99, v104, v105
	s_nop 0
	v_cvt_pk_bf16_f32 v100, v100, v101
	v_cvt_pk_bf16_f32 v101, v106, v107
	global_store_dwordx4 v[114:115], v[98:101], off offset:256
	ds_read_b32 v100, v147 offset:128
	s_waitcnt lgkmcnt(0)
	v_pk_mul_f32 v[96:97], v[96:97], v[100:101] op_sel_hi:[1,0]
	v_or_b32_e32 v98, 32, v144
	v_ashrrev_i32_e32 v99, 31, v98
	v_lshlrev_b64 v[98:99], 9, v[98:99]
	v_lshl_add_u64 v[98:99], s[20:21], 0, v[98:99]
	v_lshl_add_u64 v[98:99], v[98:99], 0, v[150:151]
	v_pk_mul_f32 v[94:95], v[94:95], v[100:101] op_sel_hi:[1,0]
	v_pk_mul_f32 v[102:103], v[92:93], v[100:101] op_sel_hi:[1,0]
	v_pk_mul_f32 v[92:93], v[90:91], v[100:101] op_sel_hi:[1,0]
	v_cvt_pk_bf16_f32 v90, v94, v95
	v_cvt_pk_bf16_f32 v91, v96, v97
	v_pk_mul_f32 v[88:89], v[88:89], v[100:101] op_sel_hi:[1,0]
	v_cvt_pk_bf16_f32 v92, v92, v93
	v_cvt_pk_bf16_f32 v93, v102, v103
	global_store_dwordx4 v[98:99], v[90:93], off
	v_pk_mul_f32 v[86:87], v[86:87], v[100:101] op_sel_hi:[1,0]
	s_nop 0
	v_pk_mul_f32 v[90:91], v[84:85], v[100:101] op_sel_hi:[1,0]
	v_pk_mul_f32 v[84:85], v[82:83], v[100:101] op_sel_hi:[1,0]
	v_cvt_pk_bf16_f32 v82, v86, v87
	v_cvt_pk_bf16_f32 v83, v88, v89
	s_nop 0
	v_cvt_pk_bf16_f32 v84, v84, v85
	v_cvt_pk_bf16_f32 v85, v90, v91
	global_store_dwordx4 v[98:99], v[82:85], off offset:256
	ds_read_b32 v84, v147 offset:192
	s_waitcnt lgkmcnt(0)
	v_pk_mul_f32 v[80:81], v[80:81], v[84:85] op_sel_hi:[1,0]
	v_or_b32_e32 v82, 48, v144
	v_ashrrev_i32_e32 v83, 31, v82
	v_lshlrev_b64 v[82:83], 9, v[82:83]
	v_lshl_add_u64 v[82:83], s[20:21], 0, v[82:83]
	v_lshl_add_u64 v[82:83], v[82:83], 0, v[150:151]
	v_pk_mul_f32 v[78:79], v[78:79], v[84:85] op_sel_hi:[1,0]
	v_pk_mul_f32 v[86:87], v[76:77], v[84:85] op_sel_hi:[1,0]
	v_pk_mul_f32 v[76:77], v[74:75], v[84:85] op_sel_hi:[1,0]
	v_cvt_pk_bf16_f32 v74, v78, v79
	v_cvt_pk_bf16_f32 v75, v80, v81
	v_pk_mul_f32 v[70:71], v[70:71], v[84:85] op_sel_hi:[1,0]
	v_cvt_pk_bf16_f32 v76, v76, v77
	v_cvt_pk_bf16_f32 v77, v86, v87
	global_store_dwordx4 v[82:83], v[74:77], off
	v_pk_mul_f32 v[72:73], v[72:73], v[84:85] op_sel_hi:[1,0]
	s_nop 0
	v_pk_mul_f32 v[74:75], v[68:69], v[84:85] op_sel_hi:[1,0]
	v_pk_mul_f32 v[68:69], v[66:67], v[84:85] op_sel_hi:[1,0]
	v_cvt_pk_bf16_f32 v66, v70, v71
	v_cvt_pk_bf16_f32 v67, v72, v73
	s_nop 0
	v_cvt_pk_bf16_f32 v68, v68, v69
	v_cvt_pk_bf16_f32 v69, v74, v75
	ds_read_b32 v70, v147 offset:512
	global_store_dwordx4 v[82:83], v[66:69], off offset:256
	s_waitcnt lgkmcnt(0)
	v_pk_mul_f32 v[62:63], v[62:63], v[70:71] op_sel_hi:[1,0]
	v_pk_mul_f32 v[66:67], v[60:61], v[70:71] op_sel_hi:[1,0]
	v_pk_mul_f32 v[60:61], v[58:59], v[70:71] op_sel_hi:[1,0]
	v_cvt_pk_bf16_f32 v58, v62, v63
	v_add_co_u32_e32 v62, vcc, s33, v130
	v_pk_mul_f32 v[64:65], v[64:65], v[70:71] op_sel_hi:[1,0]
	s_nop 0
	v_addc_co_u32_e32 v63, vcc, 0, v131, vcc
	v_cvt_pk_bf16_f32 v59, v64, v65
	v_cvt_pk_bf16_f32 v60, v60, v61
	v_cvt_pk_bf16_f32 v61, v66, v67
	global_store_dwordx4 v[62:63], v[58:61], off
	v_pk_mul_f32 v[54:55], v[54:55], v[70:71] op_sel_hi:[1,0]
	v_pk_mul_f32 v[56:57], v[56:57], v[70:71] op_sel_hi:[1,0]
	v_pk_mul_f32 v[58:59], v[52:53], v[70:71] op_sel_hi:[1,0]
	v_pk_mul_f32 v[52:53], v[50:51], v[70:71] op_sel_hi:[1,0]
	v_cvt_pk_bf16_f32 v50, v54, v55
	v_cvt_pk_bf16_f32 v51, v56, v57
	v_lshl_add_u64 v[56:57], v[130:131], 0, s[8:9]
	v_cvt_pk_bf16_f32 v52, v52, v53
	v_cvt_pk_bf16_f32 v53, v58, v59
	ds_read_b32 v54, v147 offset:576
	global_store_dwordx4 v[56:57], v[50:53], off offset:256
	s_mov_b64 s[8:9], 0x12000
	s_waitcnt lgkmcnt(0)
	v_pk_mul_f32 v[46:47], v[46:47], v[54:55] op_sel_hi:[1,0]
	v_pk_mul_f32 v[50:51], v[44:45], v[54:55] op_sel_hi:[1,0]
	v_pk_mul_f32 v[44:45], v[42:43], v[54:55] op_sel_hi:[1,0]
	v_cvt_pk_bf16_f32 v42, v46, v47
	v_add_co_u32_e32 v46, vcc, s3, v130
	v_pk_mul_f32 v[48:49], v[48:49], v[54:55] op_sel_hi:[1,0]
	s_nop 0
	v_addc_co_u32_e32 v47, vcc, 0, v131, vcc
	v_cvt_pk_bf16_f32 v43, v48, v49
	v_cvt_pk_bf16_f32 v44, v44, v45
	v_cvt_pk_bf16_f32 v45, v50, v51
	global_store_dwordx4 v[46:47], v[42:45], off
	v_pk_mul_f32 v[38:39], v[38:39], v[54:55] op_sel_hi:[1,0]
	v_pk_mul_f32 v[40:41], v[40:41], v[54:55] op_sel_hi:[1,0]
	v_pk_mul_f32 v[42:43], v[36:37], v[54:55] op_sel_hi:[1,0]
	v_pk_mul_f32 v[36:37], v[34:35], v[54:55] op_sel_hi:[1,0]
	v_cvt_pk_bf16_f32 v34, v38, v39
	v_cvt_pk_bf16_f32 v35, v40, v41
	v_lshl_add_u64 v[40:41], v[130:131], 0, s[8:9]
	v_cvt_pk_bf16_f32 v36, v36, v37
	v_cvt_pk_bf16_f32 v37, v42, v43
	ds_read_b32 v38, v147 offset:640
	global_store_dwordx4 v[40:41], v[34:37], off offset:256
	s_mov_b64 s[8:9], 0x14000
	s_waitcnt lgkmcnt(0)
	v_pk_mul_f32 v[30:31], v[30:31], v[38:39] op_sel_hi:[1,0]
	v_pk_mul_f32 v[34:35], v[28:29], v[38:39] op_sel_hi:[1,0]
	v_pk_mul_f32 v[28:29], v[26:27], v[38:39] op_sel_hi:[1,0]
	v_cvt_pk_bf16_f32 v26, v30, v31
	v_add_co_u32_e32 v30, vcc, s2, v130
	v_pk_mul_f32 v[32:33], v[32:33], v[38:39] op_sel_hi:[1,0]
	s_nop 0
	v_addc_co_u32_e32 v31, vcc, 0, v131, vcc
	v_cvt_pk_bf16_f32 v27, v32, v33
	v_cvt_pk_bf16_f32 v28, v28, v29
	v_cvt_pk_bf16_f32 v29, v34, v35
	global_store_dwordx4 v[30:31], v[26:29], off
	v_pk_mul_f32 v[22:23], v[22:23], v[38:39] op_sel_hi:[1,0]
	v_pk_mul_f32 v[24:25], v[24:25], v[38:39] op_sel_hi:[1,0]
	v_pk_mul_f32 v[26:27], v[20:21], v[38:39] op_sel_hi:[1,0]
	v_pk_mul_f32 v[20:21], v[18:19], v[38:39] op_sel_hi:[1,0]
	v_cvt_pk_bf16_f32 v18, v22, v23
	v_cvt_pk_bf16_f32 v19, v24, v25
	v_lshl_add_u64 v[24:25], v[130:131], 0, s[8:9]
	v_cvt_pk_bf16_f32 v20, v20, v21
	v_cvt_pk_bf16_f32 v21, v26, v27
	ds_read_b32 v22, v147 offset:704
	global_store_dwordx4 v[24:25], v[18:21], off offset:256
	s_mov_b64 s[8:9], 0x16000
	s_waitcnt lgkmcnt(0)
	v_pk_mul_f32 v[14:15], v[14:15], v[22:23] op_sel_hi:[1,0]
	v_pk_mul_f32 v[20:21], v[12:13], v[22:23] op_sel_hi:[1,0]
	v_pk_mul_f32 v[12:13], v[10:11], v[22:23] op_sel_hi:[1,0]
	v_cvt_pk_bf16_f32 v10, v14, v15
	v_add_co_u32_e32 v14, vcc, s80, v130
	v_pk_mul_f32 v[16:17], v[16:17], v[22:23] op_sel_hi:[1,0]
	s_nop 0
	v_addc_co_u32_e32 v15, vcc, 0, v131, vcc
	v_cvt_pk_bf16_f32 v11, v16, v17
	v_cvt_pk_bf16_f32 v12, v12, v13
	v_cvt_pk_bf16_f32 v13, v20, v21
	global_store_dwordx4 v[14:15], v[10:13], off
	v_lshl_add_u64 v[18:19], v[130:131], 0, s[8:9]
	v_pk_mul_f32 v[8:9], v[8:9], v[22:23] op_sel_hi:[1,0]
	v_pk_mul_f32 v[10:11], v[4:5], v[22:23] op_sel_hi:[1,0]
	v_pk_mul_f32 v[4:5], v[2:3], v[22:23] op_sel_hi:[1,0]
	v_pk_mul_f32 v[6:7], v[6:7], v[22:23] op_sel_hi:[1,0]
	s_andn2_b64 vcc, exec, s[0:1]
	v_cvt_pk_bf16_f32 v2, v6, v7
	v_cvt_pk_bf16_f32 v3, v8, v9
	v_cvt_pk_bf16_f32 v4, v4, v5
	v_cvt_pk_bf16_f32 v5, v10, v11
	s_mov_b64 s[0:1], -1
	global_store_dwordx4 v[18:19], v[2:5], off offset:256
	s_cbranch_vccnz .LBB0_451
	s_andn2_b64 vcc, exec, s[6:7]
	v_mov_b64 v[126:127], 0
	v_mov_b64 v[128:129], 0
	v_mov_b64 v[118:119], 0
	v_mov_b64 v[120:121], 0
	v_mov_b64 v[122:123], 0
	v_mov_b64 v[124:125], 0
	v_mfma_f32_32x32x16_bf16 v[102:117], v[126:129], v[126:129], 0
	v_mfma_f32_32x32x16_bf16 v[86:101], v[126:129], v[126:129], 0
	v_mfma_f32_32x32x16_bf16 v[70:85], v[126:129], v[126:129], 0
	v_mfma_f32_32x32x16_bf16 v[54:69], v[126:129], v[126:129], 0
	v_mfma_f32_32x32x16_bf16 v[38:53], v[126:129], v[126:129], 0
	v_mfma_f32_32x32x16_bf16 v[22:37], v[126:129], v[126:129], 0
	v_mfma_f32_32x32x16_bf16 v[6:21], v[126:129], v[126:129], 0
	v_mov_b64 v[2:3], 0
	v_mov_b64 v[4:5], 0
	s_cbranch_vccnz .LBB0_450
	s_barrier
	s_branch .LBB0_450

.LBB0_542:
	s_andn2_b64 vcc, exec, s[40:41]
	s_mov_b64 s[0:1], -1
	s_cbranch_vccnz .LBB0_481
	s_andn2_b64 vcc, exec, s[4:5]
	v_mov_b64 v[126:127], 0
	v_mov_b64 v[128:129], 0
	v_mov_b64 v[118:119], 0
	v_mov_b64 v[120:121], 0
	v_mov_b64 v[122:123], 0
	v_mov_b64 v[124:125], 0
	v_mfma_f32_32x32x16_bf16 v[102:117], v[126:129], v[126:129], 0
	v_mfma_f32_32x32x16_bf16 v[86:101], v[126:129], v[126:129], 0
	v_mfma_f32_32x32x16_bf16 v[70:85], v[126:129], v[126:129], 0
	v_mfma_f32_32x32x16_bf16 v[54:69], v[126:129], v[126:129], 0
	v_mfma_f32_32x32x16_bf16 v[38:53], v[126:129], v[126:129], 0
	v_mfma_f32_32x32x16_bf16 v[22:37], v[126:129], v[126:129], 0
	v_mfma_f32_32x32x16_bf16 v[6:21], v[126:129], v[126:129], 0
	v_mov_b64 v[2:3], 0
	v_mov_b64 v[4:5], 0
	s_cbranch_vccnz .LBB0_480
	s_barrier
	s_branch .LBB0_480

.LBB0_609:
	s_add_u32 s8, s70, 0x40080
	s_addc_u32 s9, s25, 0
	s_mov_b32 m0, s65
	s_nop 0
	global_load_lds_dwordx4 v0, s[8:9]
	v_lshl_add_u32 v141, s69, 10, v136
	s_mov_b32 m0, s66
	s_nop 0
	global_load_lds_dwordx4 v133, s[8:9]
	ds_read_b32 v145, v141
	v_lshl_or_b32 v142, s68, 7, v137
	v_lshl_add_u32 v140, s34, 8, v135
	v_ashrrev_i32_e32 v143, 31, v142
	v_mov_b64_e32 v[130:131], s[6:7]
	v_lshlrev_b64 v[142:143], 1, v[142:143]
	v_mad_i64_i32 v[130:131], s[8:9], v140, s87, v[130:131]
	s_lshl_b32 s8, s87, 4
	s_mov_b32 s9, 0
	v_lshl_add_u64 v[142:143], v[130:131], 0, v[142:143]
	s_waitcnt lgkmcnt(0)
	v_mul_f32_e32 v144, 0xbfb8aa3b, v145
	v_mul_f32_e32 v146, v145, v145
	ds_read_b32 v145, v141 offset:64
	v_pk_mul_f32 v[148:149], v[122:123], v[144:145] op_sel_hi:[1,0]
	v_pk_mul_f32 v[126:127], v[122:123], v[126:127]
	v_pk_mul_f32 v[150:151], v[124:125], v[144:145] op_sel_hi:[1,0]
	v_pk_mul_f32 v[128:129], v[124:125], v[128:129]
	v_exp_f32_e32 v122, v148
	v_exp_f32_e32 v123, v149
	v_pk_mul_f32 v[126:127], v[126:127], v[146:147] op_sel_hi:[1,0]
	v_exp_f32_e32 v124, v150
	v_exp_f32_e32 v125, v151
	v_pk_mul_f32 v[128:129], v[128:129], v[146:147] op_sel_hi:[1,0]
	v_pk_mul_f32 v[148:149], v[114:115], v[144:145] op_sel_hi:[1,0]
	v_pk_mul_f32 v[118:119], v[114:115], v[118:119]
	v_pk_add_f32 v[122:123], v[122:123], 1.0 op_sel_hi:[1,0]
	v_pk_mul_f32 v[150:151], v[116:117], v[144:145] op_sel_hi:[1,0]
	v_pk_mul_f32 v[120:121], v[116:117], v[120:121]
	v_pk_add_f32 v[124:125], v[124:125], 1.0 op_sel_hi:[1,0]
	v_rcp_f32_e32 v122, v122
	v_rcp_f32_e32 v123, v123
	v_exp_f32_e32 v114, v148
	v_exp_f32_e32 v115, v149
	v_pk_mul_f32 v[118:119], v[118:119], v[146:147] op_sel_hi:[1,0]
	v_rcp_f32_e32 v124, v124
	v_rcp_f32_e32 v125, v125
	v_exp_f32_e32 v116, v150
	v_exp_f32_e32 v117, v151
	v_pk_mul_f32 v[120:121], v[120:121], v[146:147] op_sel_hi:[1,0]
	v_pk_mul_f32 v[126:127], v[126:127], v[122:123]
	v_pk_add_f32 v[114:115], v[114:115], 1.0 op_sel_hi:[1,0]
	v_pk_mul_f32 v[128:129], v[128:129], v[124:125]
	v_pk_add_f32 v[116:117], v[116:117], 1.0 op_sel_hi:[1,0]
	v_rcp_f32_e32 v114, v114
	v_rcp_f32_e32 v115, v115
	v_rcp_f32_e32 v116, v116
	v_rcp_f32_e32 v117, v117
	v_cvt_pk_bf16_f32 v122, v126, v127
	v_cvt_pk_bf16_f32 v123, v128, v129
	v_pk_mul_f32 v[118:119], v[118:119], v[114:115]
	v_pk_mul_f32 v[120:121], v[120:121], v[116:117]
	v_cvt_pk_bf16_f32 v124, v118, v119
	v_cvt_pk_bf16_f32 v125, v120, v121
	global_store_dwordx4 v[142:143], v[122:125], off
	s_waitcnt lgkmcnt(0)
	v_mul_f32_e32 v144, 0xbfb8aa3b, v145
	v_mul_f32_e32 v146, v145, v145
	ds_read_b32 v145, v141 offset:128
	v_lshl_add_u64 v[142:143], v[142:143], 0, s[8:9]
	v_pk_mul_f32 v[148:149], v[106:107], v[144:145] op_sel_hi:[1,0]
	v_pk_mul_f32 v[110:111], v[106:107], v[110:111]
	v_pk_mul_f32 v[150:151], v[108:109], v[144:145] op_sel_hi:[1,0]
	v_pk_mul_f32 v[112:113], v[108:109], v[112:113]
	v_exp_f32_e32 v106, v148
	v_exp_f32_e32 v107, v149
	v_pk_mul_f32 v[110:111], v[110:111], v[146:147] op_sel_hi:[1,0]
	v_exp_f32_e32 v108, v150
	v_exp_f32_e32 v109, v151
	v_pk_mul_f32 v[112:113], v[112:113], v[146:147] op_sel_hi:[1,0]
	v_pk_mul_f32 v[148:149], v[98:99], v[144:145] op_sel_hi:[1,0]
	v_pk_mul_f32 v[102:103], v[98:99], v[102:103]
	v_pk_add_f32 v[106:107], v[106:107], 1.0 op_sel_hi:[1,0]
	v_pk_mul_f32 v[150:151], v[100:101], v[144:145] op_sel_hi:[1,0]
	v_pk_mul_f32 v[104:105], v[100:101], v[104:105]
	v_pk_add_f32 v[108:109], v[108:109], 1.0 op_sel_hi:[1,0]
	v_rcp_f32_e32 v106, v106
	v_rcp_f32_e32 v107, v107
	v_exp_f32_e32 v98, v148
	v_exp_f32_e32 v99, v149
	v_pk_mul_f32 v[102:103], v[102:103], v[146:147] op_sel_hi:[1,0]
	v_rcp_f32_e32 v108, v108
	v_rcp_f32_e32 v109, v109
	v_exp_f32_e32 v100, v150
	v_exp_f32_e32 v101, v151
	v_pk_mul_f32 v[104:105], v[104:105], v[146:147] op_sel_hi:[1,0]
	v_pk_mul_f32 v[110:111], v[110:111], v[106:107]
	v_pk_add_f32 v[98:99], v[98:99], 1.0 op_sel_hi:[1,0]
	v_pk_mul_f32 v[112:113], v[112:113], v[108:109]
	v_pk_add_f32 v[100:101], v[100:101], 1.0 op_sel_hi:[1,0]
	v_rcp_f32_e32 v98, v98
	v_rcp_f32_e32 v99, v99
	v_rcp_f32_e32 v100, v100
	v_rcp_f32_e32 v101, v101
	v_cvt_pk_bf16_f32 v106, v110, v111
	v_cvt_pk_bf16_f32 v107, v112, v113
	v_pk_mul_f32 v[102:103], v[102:103], v[98:99]
	v_pk_mul_f32 v[104:105], v[104:105], v[100:101]
	v_cvt_pk_bf16_f32 v108, v102, v103
	v_cvt_pk_bf16_f32 v109, v104, v105
	global_store_dwordx4 v[142:143], v[106:109], off
	s_waitcnt lgkmcnt(0)
	v_mul_f32_e32 v144, 0xbfb8aa3b, v145
	v_mul_f32_e32 v146, v145, v145
	ds_read_b32 v145, v141 offset:192
	v_lshl_add_u64 v[142:143], v[142:143], 0, s[8:9]
	v_pk_mul_f32 v[148:149], v[90:91], v[144:145] op_sel_hi:[1,0]
	v_pk_mul_f32 v[94:95], v[90:91], v[94:95]
	v_pk_mul_f32 v[150:151], v[92:93], v[144:145] op_sel_hi:[1,0]
	v_pk_mul_f32 v[96:97], v[92:93], v[96:97]
	v_exp_f32_e32 v90, v148
	v_exp_f32_e32 v91, v149
	v_pk_mul_f32 v[94:95], v[94:95], v[146:147] op_sel_hi:[1,0]
	v_exp_f32_e32 v92, v150
	v_exp_f32_e32 v93, v151
	v_pk_mul_f32 v[96:97], v[96:97], v[146:147] op_sel_hi:[1,0]
	v_pk_mul_f32 v[148:149], v[82:83], v[144:145] op_sel_hi:[1,0]
	v_pk_mul_f32 v[86:87], v[82:83], v[86:87]
	v_pk_add_f32 v[90:91], v[90:91], 1.0 op_sel_hi:[1,0]
	v_pk_mul_f32 v[150:151], v[84:85], v[144:145] op_sel_hi:[1,0]
	v_pk_mul_f32 v[88:89], v[84:85], v[88:89]
	v_pk_add_f32 v[92:93], v[92:93], 1.0 op_sel_hi:[1,0]
	v_rcp_f32_e32 v90, v90
	v_rcp_f32_e32 v91, v91
	v_exp_f32_e32 v82, v148
	v_exp_f32_e32 v83, v149
	v_pk_mul_f32 v[86:87], v[86:87], v[146:147] op_sel_hi:[1,0]
	v_rcp_f32_e32 v92, v92
	v_rcp_f32_e32 v93, v93
	v_exp_f32_e32 v84, v150
	v_exp_f32_e32 v85, v151
	v_pk_mul_f32 v[88:89], v[88:89], v[146:147] op_sel_hi:[1,0]
	v_pk_mul_f32 v[94:95], v[94:95], v[90:91]
	v_pk_add_f32 v[82:83], v[82:83], 1.0 op_sel_hi:[1,0]
	v_pk_mul_f32 v[96:97], v[96:97], v[92:93]
	v_pk_add_f32 v[84:85], v[84:85], 1.0 op_sel_hi:[1,0]
	v_rcp_f32_e32 v82, v82
	v_rcp_f32_e32 v83, v83
	v_rcp_f32_e32 v84, v84
	v_rcp_f32_e32 v85, v85
	v_cvt_pk_bf16_f32 v90, v94, v95
	v_cvt_pk_bf16_f32 v91, v96, v97
	v_pk_mul_f32 v[86:87], v[86:87], v[82:83]
	v_pk_mul_f32 v[88:89], v[88:89], v[84:85]
	v_cvt_pk_bf16_f32 v92, v86, v87
	v_cvt_pk_bf16_f32 v93, v88, v89
	global_store_dwordx4 v[142:143], v[90:93], off
	s_waitcnt lgkmcnt(0)
	v_mul_f32_e32 v144, 0xbfb8aa3b, v145
	v_mul_f32_e32 v146, v145, v145
	ds_read_b32 v145, v141 offset:512
	v_lshl_add_u64 v[142:143], v[142:143], 0, s[8:9]
	s_mul_i32 s8, s87, 0x50
	v_pk_mul_f32 v[148:149], v[74:75], v[144:145] op_sel_hi:[1,0]
	v_pk_mul_f32 v[78:79], v[74:75], v[78:79]
	v_pk_mul_f32 v[150:151], v[76:77], v[144:145] op_sel_hi:[1,0]
	v_pk_mul_f32 v[80:81], v[76:77], v[80:81]
	v_exp_f32_e32 v74, v148
	v_exp_f32_e32 v75, v149
	v_pk_mul_f32 v[78:79], v[78:79], v[146:147] op_sel_hi:[1,0]
	v_exp_f32_e32 v76, v150
	v_exp_f32_e32 v77, v151
	v_pk_mul_f32 v[80:81], v[80:81], v[146:147] op_sel_hi:[1,0]
	v_pk_mul_f32 v[148:149], v[66:67], v[144:145] op_sel_hi:[1,0]
	v_pk_mul_f32 v[70:71], v[66:67], v[70:71]
	v_pk_add_f32 v[74:75], v[74:75], 1.0 op_sel_hi:[1,0]
	v_pk_mul_f32 v[150:151], v[68:69], v[144:145] op_sel_hi:[1,0]
	v_pk_mul_f32 v[72:73], v[68:69], v[72:73]
	v_pk_add_f32 v[76:77], v[76:77], 1.0 op_sel_hi:[1,0]
	v_rcp_f32_e32 v74, v74
	v_rcp_f32_e32 v75, v75
	v_exp_f32_e32 v66, v148
	v_exp_f32_e32 v67, v149
	v_pk_mul_f32 v[70:71], v[70:71], v[146:147] op_sel_hi:[1,0]
	v_rcp_f32_e32 v76, v76
	v_rcp_f32_e32 v77, v77
	v_exp_f32_e32 v68, v150
	v_exp_f32_e32 v69, v151
	v_pk_mul_f32 v[72:73], v[72:73], v[146:147] op_sel_hi:[1,0]
	v_pk_mul_f32 v[78:79], v[78:79], v[74:75]
	v_pk_add_f32 v[66:67], v[66:67], 1.0 op_sel_hi:[1,0]
	v_pk_mul_f32 v[80:81], v[80:81], v[76:77]
	v_pk_add_f32 v[68:69], v[68:69], 1.0 op_sel_hi:[1,0]
	v_rcp_f32_e32 v66, v66
	v_rcp_f32_e32 v67, v67
	v_rcp_f32_e32 v68, v68
	v_rcp_f32_e32 v69, v69
	v_cvt_pk_bf16_f32 v74, v78, v79
	v_cvt_pk_bf16_f32 v75, v80, v81
	v_pk_mul_f32 v[70:71], v[70:71], v[66:67]
	v_pk_mul_f32 v[72:73], v[72:73], v[68:69]
	v_cvt_pk_bf16_f32 v76, v70, v71
	v_cvt_pk_bf16_f32 v77, v72, v73
	global_store_dwordx4 v[142:143], v[74:77], off
	s_waitcnt lgkmcnt(0)
	v_mul_f32_e32 v144, 0xbfb8aa3b, v145
	v_mul_f32_e32 v146, v145, v145
	ds_read_b32 v145, v141 offset:576
	v_lshl_add_u64 v[142:143], v[142:143], 0, s[8:9]
	s_lshl_b32 s8, s87, 4
	v_pk_mul_f32 v[148:149], v[58:59], v[144:145] op_sel_hi:[1,0]
	v_pk_mul_f32 v[62:63], v[58:59], v[62:63]
	v_pk_mul_f32 v[150:151], v[60:61], v[144:145] op_sel_hi:[1,0]
	v_pk_mul_f32 v[64:65], v[60:61], v[64:65]
	v_exp_f32_e32 v58, v148
	v_exp_f32_e32 v59, v149
	v_pk_mul_f32 v[62:63], v[62:63], v[146:147] op_sel_hi:[1,0]
	v_exp_f32_e32 v60, v150
	v_exp_f32_e32 v61, v151
	v_pk_mul_f32 v[64:65], v[64:65], v[146:147] op_sel_hi:[1,0]
	v_pk_mul_f32 v[148:149], v[50:51], v[144:145] op_sel_hi:[1,0]
	v_pk_mul_f32 v[54:55], v[50:51], v[54:55]
	v_pk_add_f32 v[58:59], v[58:59], 1.0 op_sel_hi:[1,0]
	v_pk_mul_f32 v[150:151], v[52:53], v[144:145] op_sel_hi:[1,0]
	v_pk_mul_f32 v[56:57], v[52:53], v[56:57]
	v_pk_add_f32 v[60:61], v[60:61], 1.0 op_sel_hi:[1,0]
	v_rcp_f32_e32 v58, v58
	v_rcp_f32_e32 v59, v59
	v_exp_f32_e32 v50, v148
	v_exp_f32_e32 v51, v149
	v_pk_mul_f32 v[54:55], v[54:55], v[146:147] op_sel_hi:[1,0]
	v_rcp_f32_e32 v60, v60
	v_rcp_f32_e32 v61, v61
	v_exp_f32_e32 v52, v150
	v_exp_f32_e32 v53, v151
	v_pk_mul_f32 v[56:57], v[56:57], v[146:147] op_sel_hi:[1,0]
	v_pk_mul_f32 v[62:63], v[62:63], v[58:59]
	v_pk_add_f32 v[50:51], v[50:51], 1.0 op_sel_hi:[1,0]
	v_pk_mul_f32 v[64:65], v[64:65], v[60:61]
	v_pk_add_f32 v[52:53], v[52:53], 1.0 op_sel_hi:[1,0]
	v_rcp_f32_e32 v50, v50
	v_rcp_f32_e32 v51, v51
	v_rcp_f32_e32 v52, v52
	v_rcp_f32_e32 v53, v53
	v_cvt_pk_bf16_f32 v58, v62, v63
	v_cvt_pk_bf16_f32 v59, v64, v65
	v_pk_mul_f32 v[54:55], v[54:55], v[50:51]
	v_pk_mul_f32 v[56:57], v[56:57], v[52:53]
	v_cvt_pk_bf16_f32 v60, v54, v55
	v_cvt_pk_bf16_f32 v61, v56, v57
	global_store_dwordx4 v[142:143], v[58:61], off
	s_waitcnt lgkmcnt(0)
	v_mul_f32_e32 v144, 0xbfb8aa3b, v145
	v_mul_f32_e32 v146, v145, v145
	ds_read_b32 v145, v141 offset:640
	v_lshl_add_u64 v[142:143], v[142:143], 0, s[8:9]
	v_pk_mul_f32 v[148:149], v[42:43], v[144:145] op_sel_hi:[1,0]
	v_pk_mul_f32 v[46:47], v[42:43], v[46:47]
	v_pk_mul_f32 v[150:151], v[44:45], v[144:145] op_sel_hi:[1,0]
	v_pk_mul_f32 v[48:49], v[44:45], v[48:49]
	v_exp_f32_e32 v42, v148
	v_exp_f32_e32 v43, v149
	v_pk_mul_f32 v[46:47], v[46:47], v[146:147] op_sel_hi:[1,0]
	v_exp_f32_e32 v44, v150
	v_exp_f32_e32 v45, v151
	v_pk_mul_f32 v[48:49], v[48:49], v[146:147] op_sel_hi:[1,0]
	v_pk_mul_f32 v[148:149], v[34:35], v[144:145] op_sel_hi:[1,0]
	v_pk_mul_f32 v[38:39], v[34:35], v[38:39]
	v_pk_add_f32 v[42:43], v[42:43], 1.0 op_sel_hi:[1,0]
	v_pk_mul_f32 v[150:151], v[36:37], v[144:145] op_sel_hi:[1,0]
	v_pk_mul_f32 v[40:41], v[36:37], v[40:41]
	v_pk_add_f32 v[44:45], v[44:45], 1.0 op_sel_hi:[1,0]
	v_rcp_f32_e32 v42, v42
	v_rcp_f32_e32 v43, v43
	v_exp_f32_e32 v34, v148
	v_exp_f32_e32 v35, v149
	v_pk_mul_f32 v[38:39], v[38:39], v[146:147] op_sel_hi:[1,0]
	v_rcp_f32_e32 v44, v44
	v_rcp_f32_e32 v45, v45
	v_exp_f32_e32 v36, v150
	v_exp_f32_e32 v37, v151
	v_pk_mul_f32 v[40:41], v[40:41], v[146:147] op_sel_hi:[1,0]
	v_pk_mul_f32 v[46:47], v[46:47], v[42:43]
	v_pk_add_f32 v[34:35], v[34:35], 1.0 op_sel_hi:[1,0]
	v_pk_mul_f32 v[48:49], v[48:49], v[44:45]
	v_pk_add_f32 v[36:37], v[36:37], 1.0 op_sel_hi:[1,0]
	v_rcp_f32_e32 v34, v34
	v_rcp_f32_e32 v35, v35
	v_rcp_f32_e32 v36, v36
	v_rcp_f32_e32 v37, v37
	v_cvt_pk_bf16_f32 v42, v46, v47
	v_cvt_pk_bf16_f32 v43, v48, v49
	v_pk_mul_f32 v[38:39], v[38:39], v[34:35]
	v_pk_mul_f32 v[40:41], v[40:41], v[36:37]
	v_cvt_pk_bf16_f32 v44, v38, v39
	v_cvt_pk_bf16_f32 v45, v40, v41
	global_store_dwordx4 v[142:143], v[42:45], off
	s_waitcnt lgkmcnt(0)
	v_mul_f32_e32 v144, 0xbfb8aa3b, v145
	v_mul_f32_e32 v146, v145, v145
	ds_read_b32 v145, v141 offset:704
	v_lshl_add_u64 v[142:143], v[142:143], 0, s[8:9]
	v_pk_mul_f32 v[148:149], v[26:27], v[144:145] op_sel_hi:[1,0]
	v_pk_mul_f32 v[30:31], v[26:27], v[30:31]
	v_pk_mul_f32 v[150:151], v[28:29], v[144:145] op_sel_hi:[1,0]
	v_pk_mul_f32 v[32:33], v[28:29], v[32:33]
	v_exp_f32_e32 v26, v148
	v_exp_f32_e32 v27, v149
	v_pk_mul_f32 v[30:31], v[30:31], v[146:147] op_sel_hi:[1,0]
	v_exp_f32_e32 v28, v150
	v_exp_f32_e32 v29, v151
	v_pk_mul_f32 v[32:33], v[32:33], v[146:147] op_sel_hi:[1,0]
	v_pk_mul_f32 v[148:149], v[18:19], v[144:145] op_sel_hi:[1,0]
	v_pk_mul_f32 v[22:23], v[18:19], v[22:23]
	v_pk_add_f32 v[26:27], v[26:27], 1.0 op_sel_hi:[1,0]
	v_pk_mul_f32 v[150:151], v[20:21], v[144:145] op_sel_hi:[1,0]
	v_pk_mul_f32 v[24:25], v[20:21], v[24:25]
	v_pk_add_f32 v[28:29], v[28:29], 1.0 op_sel_hi:[1,0]
	v_rcp_f32_e32 v26, v26
	v_rcp_f32_e32 v27, v27
	v_exp_f32_e32 v18, v148
	v_exp_f32_e32 v19, v149
	v_pk_mul_f32 v[22:23], v[22:23], v[146:147] op_sel_hi:[1,0]
	v_rcp_f32_e32 v28, v28
	v_rcp_f32_e32 v29, v29
	v_exp_f32_e32 v20, v150
	v_exp_f32_e32 v21, v151
	v_pk_mul_f32 v[24:25], v[24:25], v[146:147] op_sel_hi:[1,0]
	v_pk_mul_f32 v[30:31], v[30:31], v[26:27]
	v_pk_add_f32 v[18:19], v[18:19], 1.0 op_sel_hi:[1,0]
	v_pk_mul_f32 v[32:33], v[32:33], v[28:29]
	v_pk_add_f32 v[20:21], v[20:21], 1.0 op_sel_hi:[1,0]
	v_rcp_f32_e32 v18, v18
	v_rcp_f32_e32 v19, v19
	v_rcp_f32_e32 v20, v20
	v_rcp_f32_e32 v21, v21
	v_cvt_pk_bf16_f32 v26, v30, v31
	v_cvt_pk_bf16_f32 v27, v32, v33
	v_pk_mul_f32 v[22:23], v[22:23], v[18:19]
	v_pk_mul_f32 v[24:25], v[24:25], v[20:21]
	v_cvt_pk_bf16_f32 v28, v22, v23
	v_cvt_pk_bf16_f32 v29, v24, v25
	global_store_dwordx4 v[142:143], v[26:29], off
	s_waitcnt lgkmcnt(0)
	v_mul_f32_e32 v144, 0xbfb8aa3b, v145
	v_mul_f32_e32 v146, v145, v145
	v_lshl_add_u64 v[142:143], v[142:143], 0, s[8:9]
	v_pk_mul_f32 v[148:149], v[10:11], v[144:145] op_sel_hi:[1,0]
	v_pk_mul_f32 v[14:15], v[10:11], v[14:15]
	v_pk_mul_f32 v[150:151], v[12:13], v[144:145] op_sel_hi:[1,0]
	v_pk_mul_f32 v[16:17], v[12:13], v[16:17]
	v_exp_f32_e32 v10, v148
	v_exp_f32_e32 v11, v149
	v_pk_mul_f32 v[14:15], v[14:15], v[146:147] op_sel_hi:[1,0]
	v_exp_f32_e32 v12, v150
	v_exp_f32_e32 v13, v151
	v_pk_mul_f32 v[16:17], v[16:17], v[146:147] op_sel_hi:[1,0]
	v_pk_mul_f32 v[148:149], v[2:3], v[144:145] op_sel_hi:[1,0]
	v_pk_mul_f32 v[6:7], v[2:3], v[6:7]
	v_pk_add_f32 v[10:11], v[10:11], 1.0 op_sel_hi:[1,0]
	v_pk_mul_f32 v[150:151], v[4:5], v[144:145] op_sel_hi:[1,0]
	v_pk_mul_f32 v[8:9], v[4:5], v[8:9]
	v_pk_add_f32 v[12:13], v[12:13], 1.0 op_sel_hi:[1,0]
	v_rcp_f32_e32 v10, v10
	v_rcp_f32_e32 v11, v11
	v_exp_f32_e32 v2, v148
	v_exp_f32_e32 v3, v149
	v_pk_mul_f32 v[6:7], v[6:7], v[146:147] op_sel_hi:[1,0]
	v_rcp_f32_e32 v12, v12
	v_rcp_f32_e32 v13, v13
	v_exp_f32_e32 v4, v150
	v_exp_f32_e32 v5, v151
	v_pk_mul_f32 v[8:9], v[8:9], v[146:147] op_sel_hi:[1,0]
	v_pk_mul_f32 v[14:15], v[14:15], v[10:11]
	v_pk_add_f32 v[2:3], v[2:3], 1.0 op_sel_hi:[1,0]
	v_pk_mul_f32 v[16:17], v[16:17], v[12:13]
	v_pk_add_f32 v[4:5], v[4:5], 1.0 op_sel_hi:[1,0]
	v_rcp_f32_e32 v2, v2
	v_rcp_f32_e32 v3, v3
	v_rcp_f32_e32 v4, v4
	v_rcp_f32_e32 v5, v5
	v_cvt_pk_bf16_f32 v10, v14, v15
	v_cvt_pk_bf16_f32 v11, v16, v17
	v_pk_mul_f32 v[6:7], v[6:7], v[2:3]
	v_pk_mul_f32 v[8:9], v[8:9], v[4:5]
	v_cvt_pk_bf16_f32 v12, v6, v7
	v_cvt_pk_bf16_f32 v13, v8, v9
	s_andn2_b64 vcc, exec, s[0:1]
	s_mov_b64 s[0:1], -1
	global_store_dwordx4 v[142:143], v[10:13], off
	s_cbranch_vccnz .LBB0_602
	s_andn2_b64 vcc, exec, s[4:5]
	v_mov_b64 v[126:127], 0
	v_mov_b64 v[128:129], 0
	v_mov_b64 v[118:119], 0
	v_mov_b64 v[120:121], 0
	v_mov_b64 v[122:123], 0
	v_mov_b64 v[124:125], 0
	v_mfma_f32_32x32x16_bf16 v[102:117], v[126:129], v[126:129], 0
	v_mfma_f32_32x32x16_bf16 v[86:101], v[126:129], v[126:129], 0
	v_mfma_f32_32x32x16_bf16 v[70:85], v[126:129], v[126:129], 0
	v_mfma_f32_32x32x16_bf16 v[54:69], v[126:129], v[126:129], 0
	v_mfma_f32_32x32x16_bf16 v[38:53], v[126:129], v[126:129], 0
	v_mfma_f32_32x32x16_bf16 v[22:37], v[126:129], v[126:129], 0
	v_mfma_f32_32x32x16_bf16 v[6:21], v[126:129], v[126:129], 0
	v_mov_b64 v[2:3], 0
	v_mov_b64 v[4:5], 0
	s_cbranch_vccnz .LBB0_601
	s_barrier
	s_branch .LBB0_601
